# v36 with the per-block s_setprio flips removed and one static s_setprio 1 for waves 0-3 during the GEMM phases (section 7.4, other half)
# speedup vs baseline: 1.0049x; 1.0049x over previous
; #define REP(k) for (int rep_ = 0; rep_ < ((DUP) == (k) ? 2 : 1); ++rep_)
;     __device__ bool next(int i, Unit& u) const {
;         if (G == 256) { if (i >= R) return false; const int xcd = c & 7, r = c >> 3; u.pm = (xcd >> 1) * 8 + (r & 7); u.pn = (2 * i + (xcd & 1)) * 4 + (r >> 3); return true; }
;         const int L = i * G + c; if (L >= 32 * 8 * R) return false; u.pm = L & 31; u.pn = L >> 5; return true;
; __global__ void __launch_bounds__(NT, 2) fwd(Args args) {
;     ...
;     REP(1) {
;         pg8::Gemm g{XB, WIN, DM, DM, DM, 0}; EpiIn E{ssq, UBF, out + O_POOLP, QB, KB, VB, out + O_FKP, out + O_FVP};
;         pg8::BalancedOrder S{2, bx, G}; pg8::gemm_phase<EpiIn, pg8::BalancedOrder, true>(lds, g, S, E);
.LBB0_99:
	s_or_b64 exec, exec, s[4:5]
	s_cmpk_lg_i32 s76, 0x100
	s_cselect_b64 s[20:21], -1, 0
	s_cmpk_gt_i32 s86, 0x1ff
	s_cselect_b64 s[18:19], -1, 0
	s_lshl_b32 s2, s86, 2
	s_and_b32 s4, s2, 24
	s_bfe_u32 s5, s86, 0x30003
	s_or_b32 s26, s4, s5
	s_and_b32 s2, s2, 4
	s_ashr_i32 s4, s86, 6
	s_ashr_i32 s24, s86, 5
	s_and_b32 s25, s86, 31
	s_add_i32 s27, s2, s4
	s_cmpk_eq_i32 s76, 0x100
	s_cselect_b64 s[22:23], -1, 0
	v_writelane_b32 v242, s22, 10
	s_mov_b64 s[10:11], s[0:1]
	s_mov_b64 s[12:13], s[0:1]
	v_writelane_b32 v242, s23, 11
	s_and_b64 s[22:23], s[22:23], exec
	s_mov_b64 s[14:15], s[0:1]
	s_mov_b64 s[6:7], s[0:1]
	s_mov_b64 s[16:17], s[0:1]
	s_mov_b64 s[4:5], s[0:1]
	s_mov_b64 s[8:9], s[0:1]
	s_mov_b64 s[28:29], s[0:1]
	s_mov_b64 s[30:31], s[0:1]
	s_mov_b64 s[34:35], s[0:1]
	s_waitcnt lgkmcnt(0)
	v_mov_b32_e32 v2, v0
	s_cselect_b32 s22, s27, s24
	s_cselect_b32 s60, s26, s25
	s_and_b64 s[18:19], s[20:21], s[18:19]
	s_barrier
	v_readlane_b32 s99, v242, 0
	s_nop 1
	s_cmp_gt_u32 s99, 3
	s_cbranch_scc1 .Lsp_0
	s_setprio 1

.LBB0_1120:
	s_or_b64 exec, exec, s[4:5]
	s_mov_b64 s[10:11], s[0:1]
	s_mov_b64 s[12:13], s[0:1]
	s_mov_b64 s[4:5], s[0:1]
	s_mov_b64 s[2:3], s[0:1]
	s_waitcnt lgkmcnt(0)
	s_barrier
	v_readlane_b32 s99, v242, 0
	s_nop 1
	s_cmp_gt_u32 s99, 3
	s_cbranch_scc1 .Lsp_3
	s_setprio 1

.LBB0_1205:
	s_or_b64 exec, exec, s[4:5]
	s_cmpk_lt_i32 s94, 0x5ac
	s_cselect_b64 s[6:7], -1, 0
	s_mov_b64 s[4:5], s[0:1]
	s_mov_b64 s[8:9], s[0:1]
	s_mov_b64 s[12:13], s[0:1]
	s_mov_b64 s[14:15], s[0:1]
	s_waitcnt lgkmcnt(0)
	v_mov_b32_e32 v2, v0
	s_barrier
	v_readlane_b32 s99, v242, 0
	s_nop 1
	s_cmp_gt_u32 s99, 3
	s_cbranch_scc1 .Lsp_4
	s_setprio 1

; #define REP(k) for (int rep_ = 0; rep_ < ((DUP) == (k) ? 2 : 1); ++rep_)
; __global__ void __launch_bounds__(NT, 2) fwd(Args args) {
;     ...
;     REP(11) {
;         pg8::Gemm g{HB, WQKV, DM, DM, DM, 0}; EpiQkv E{ssq + 2 * MPAD, QB, KB, VB, out + O_SKP, out + O_SVP};
;         pg8::BalancedOrder S{3, bx, G}; pg8::gemm_phase<EpiQkv, pg8::BalancedOrder, true>(lds, g, S, E);
.LBB0_1395:
	s_or_b64 exec, exec, s[4:5]
	s_cmpk_lt_i32 s94, 0x300
	v_readlane_b32 s18, v242, 10
	s_cselect_b64 s[6:7], -1, 0
	v_readlane_b32 s19, v242, 11
	s_mov_b64 s[12:13], s[0:1]
	s_mov_b64 s[14:15], s[0:1]
	s_mov_b64 s[16:17], s[0:1]
	s_mov_b64 s[8:9], s[0:1]
	s_mov_b64 s[26:27], s[0:1]
	s_mov_b64 s[4:5], s[0:1]
	s_mov_b64 s[10:11], s[0:1]
	s_mov_b64 s[30:31], s[0:1]
	s_waitcnt lgkmcnt(0)
	v_mov_b32_e32 v2, v0
	s_or_b64 s[6:7], s[18:19], s[6:7]
	s_barrier
	v_readlane_b32 s99, v242, 0
	s_nop 1
	s_cmp_gt_u32 s99, 3
	s_cbranch_scc1 .Lsp_6
	s_setprio 1

.LBB0_1977:
	s_or_b64 exec, exec, s[4:5]
	s_mov_b64 s[10:11], s[0:1]
	s_mov_b64 s[12:13], s[0:1]
	s_mov_b64 s[8:9], s[0:1]
	s_mov_b64 s[2:3], s[0:1]
	s_waitcnt lgkmcnt(0)
	s_barrier
	v_readlane_b32 s99, v242, 0
	s_nop 1
	s_cmp_gt_u32 s99, 3
	s_cbranch_scc1 .Lsp_8
	s_setprio 1

.LBB0_2062:
	s_or_b64 exec, exec, s[4:5]
	v_readlane_b32 s6, v242, 20
	s_mov_b64 s[4:5], s[0:1]
	s_mov_b64 s[8:9], s[0:1]
	s_mov_b64 s[12:13], s[0:1]
	s_mov_b64 s[14:15], s[0:1]
	s_waitcnt lgkmcnt(0)
	v_mov_b32_e32 v2, v0
	v_readlane_b32 s7, v242, 21
	s_barrier
	v_readlane_b32 s99, v242, 0
	s_nop 1
	s_cmp_gt_u32 s99, 3
	s_cbranch_scc1 .Lsp_9
	s_setprio 1

.LBB0_2152:
	s_or_b64 exec, exec, s[4:5]
	s_mov_b64 s[4:5], s[0:1]
	s_mov_b64 s[8:9], s[0:1]
	s_mov_b64 s[6:7], s[0:1]
	s_mov_b64 s[2:3], s[0:1]
	s_waitcnt lgkmcnt(0)
	s_barrier
	v_readlane_b32 s99, v242, 0
	s_nop 1
	s_cmp_gt_u32 s99, 3
	s_cbranch_scc1 .Lsp_10
	s_setprio 1
